# GLA gate phase hand-rewritten: 3-deep ring of half-row LDS reads issued two halves ahead, two FMA accumulators per token, exp/log chain interleaved behind next token FMAs
# speedup vs baseline: 1.0165x; 1.0165x over previous
.LBB0_537:
	v_mov_b32_e32 v40, 0
	v_mov_b32_e32 v41, 0
	v_mov_b32_e32 v42, 0
	v_mov_b32_e32 v43, 0
	v_mov_b32_e32 v44, 0
	v_mov_b32_e32 v45, 0
	v_mov_b32_e32 v46, 0
	v_mov_b32_e32 v47, 0
	s_waitcnt vmcnt(0)
	ds_write2st64_b32 v129, v193, v194 offset0:96 offset1:100
	ds_write_b16 v146, v181 offset:15872
	ds_write_b16 v148, v182 offset:15872
	ds_write_b16 v149, v183 offset:15872
	ds_write_b16 v150, v184 offset:15872
	ds_write_b16 v151, v185 offset:15872
	ds_write_b16 v152, v186 offset:15872
	ds_write_b16 v153, v187 offset:15872
	ds_write_b16 v154, v188 offset:15872
	ds_write_b16 v155, v189 offset:15872
	ds_write_b16 v156, v190 offset:15872
	ds_write_b16 v157, v191 offset:15872
	ds_write_b16 v158, v192 offset:15872
	s_waitcnt lgkmcnt(0)
	s_barrier
	s_and_saveexec_b64 s[2:3], s[8:9]
	s_cbranch_execz .LBB0_539
	s_mov_b32 s4, 0xbd800000
	ds_read_b128 v[32:35], v141 offset:24576
	ds_read_b128 v[48:51], v141 offset:24592
	ds_read_b128 v[182:185], v141 offset:24608
	ds_read_b128 v[186:189], v141 offset:24624
	ds_read_b128 v[190:193], v141 offset:24640
	ds_read_b128 v[194:197], v141 offset:24656
	s_waitcnt lgkmcnt(4)
	v_fma_f32 v52, v32, v58, v127
	v_mul_f32_e32 v53, v33, v56
	v_fmac_f32_e32 v52, v34, v62
	v_fmac_f32_e32 v53, v35, v60
	v_fmac_f32_e32 v52, v48, v59
	v_fmac_f32_e32 v53, v49, v57
	v_fmac_f32_e32 v52, v50, v63
	v_fmac_f32_e32 v53, v51, v61
	ds_read_b128 v[32:35], v141 offset:24672
	ds_read_b128 v[48:51], v141 offset:24688
	s_waitcnt lgkmcnt(4)
	v_fmac_f32_e32 v52, v182, v66
	v_fmac_f32_e32 v53, v183, v64
	v_fmac_f32_e32 v52, v184, v70
	v_fmac_f32_e32 v53, v185, v68
	v_fmac_f32_e32 v52, v186, v67
	v_fmac_f32_e32 v53, v187, v65
	v_fmac_f32_e32 v52, v188, v71
	v_fmac_f32_e32 v53, v189, v69
	ds_read_b128 v[182:185], v141 offset:24704
	ds_read_b128 v[186:189], v141 offset:24720
	v_add_f32_e32 v200, v52, v53
	v_mul_f32_e32 v200, 0xbfb8aa3b, v200
	v_exp_f32_e32 v200, v200
	s_waitcnt lgkmcnt(4)
	v_fma_f32 v198, v190, v58, v127
	v_mul_f32_e32 v199, v191, v56
	v_fmac_f32_e32 v198, v192, v62
	v_fmac_f32_e32 v199, v193, v60
	v_fmac_f32_e32 v198, v194, v59
	v_fmac_f32_e32 v199, v195, v57
	v_fmac_f32_e32 v198, v196, v63
	v_fmac_f32_e32 v199, v197, v61
	ds_read_b128 v[190:193], v141 offset:24736
	ds_read_b128 v[194:197], v141 offset:24752
	v_add_f32_e32 v200, 1.0, v200
	v_log_f32_e32 v200, v200
	s_waitcnt lgkmcnt(4)
	v_fmac_f32_e32 v198, v32, v66
	v_fmac_f32_e32 v199, v33, v64
	v_fmac_f32_e32 v198, v34, v70
	v_fmac_f32_e32 v199, v35, v68
	v_fmac_f32_e32 v198, v48, v67
	v_fmac_f32_e32 v199, v49, v65
	v_fmac_f32_e32 v198, v50, v71
	v_fmac_f32_e32 v199, v51, v69
	ds_read_b128 v[32:35], v141 offset:24768
	ds_read_b128 v[48:51], v141 offset:24784
	v_mul_f32_e32 v40, 0xbd800000, v200
	v_add_f32_e32 v201, v198, v199
	v_mul_f32_e32 v201, 0xbfb8aa3b, v201
	v_exp_f32_e32 v201, v201
	s_waitcnt lgkmcnt(4)
	v_fma_f32 v52, v182, v58, v127
	v_mul_f32_e32 v53, v183, v56
	v_fmac_f32_e32 v52, v184, v62
	v_fmac_f32_e32 v53, v185, v60
	v_fmac_f32_e32 v52, v186, v59
	v_fmac_f32_e32 v53, v187, v57
	v_fmac_f32_e32 v52, v188, v63
	v_fmac_f32_e32 v53, v189, v61
	ds_read_b128 v[182:185], v141 offset:24800
	ds_read_b128 v[186:189], v141 offset:24816
	v_add_f32_e32 v201, 1.0, v201
	v_log_f32_e32 v201, v201
	s_waitcnt lgkmcnt(4)
	v_fmac_f32_e32 v52, v190, v66
	v_fmac_f32_e32 v53, v191, v64
	v_fmac_f32_e32 v52, v192, v70
	v_fmac_f32_e32 v53, v193, v68
	v_fmac_f32_e32 v52, v194, v67
	v_fmac_f32_e32 v53, v195, v65
	v_fmac_f32_e32 v52, v196, v71
	v_fmac_f32_e32 v53, v197, v69
	ds_read_b128 v[190:193], v141 offset:24832
	ds_read_b128 v[194:197], v141 offset:24848
	v_fmamk_f32 v41, v201, 0xbd800000, v40
	v_add_f32_e32 v200, v52, v53
	v_mul_f32_e32 v200, 0xbfb8aa3b, v200
	v_exp_f32_e32 v200, v200
	s_waitcnt lgkmcnt(4)
	v_fma_f32 v198, v32, v58, v127
	v_mul_f32_e32 v199, v33, v56
	v_fmac_f32_e32 v198, v34, v62
	v_fmac_f32_e32 v199, v35, v60
	v_fmac_f32_e32 v198, v48, v59
	v_fmac_f32_e32 v199, v49, v57
	v_fmac_f32_e32 v198, v50, v63
	v_fmac_f32_e32 v199, v51, v61
	ds_read_b128 v[32:35], v141 offset:24864
	ds_read_b128 v[48:51], v141 offset:24880
	v_add_f32_e32 v200, 1.0, v200
	v_log_f32_e32 v200, v200
	s_waitcnt lgkmcnt(4)
	v_fmac_f32_e32 v198, v182, v66
	v_fmac_f32_e32 v199, v183, v64
	v_fmac_f32_e32 v198, v184, v70
	v_fmac_f32_e32 v199, v185, v68
	v_fmac_f32_e32 v198, v186, v67
	v_fmac_f32_e32 v199, v187, v65
	v_fmac_f32_e32 v198, v188, v71
	v_fmac_f32_e32 v199, v189, v69
	ds_read_b128 v[182:185], v141 offset:24896
	ds_read_b128 v[186:189], v141 offset:24912
	v_fmamk_f32 v42, v200, 0xbd800000, v41
	v_add_f32_e32 v201, v198, v199
	v_mul_f32_e32 v201, 0xbfb8aa3b, v201
	v_exp_f32_e32 v201, v201
	s_waitcnt lgkmcnt(4)
	v_fma_f32 v52, v190, v58, v127
	v_mul_f32_e32 v53, v191, v56
	v_fmac_f32_e32 v52, v192, v62
	v_fmac_f32_e32 v53, v193, v60
	v_fmac_f32_e32 v52, v194, v59
	v_fmac_f32_e32 v53, v195, v57
	v_fmac_f32_e32 v52, v196, v63
	v_fmac_f32_e32 v53, v197, v61
	ds_read_b128 v[190:193], v141 offset:24928
	ds_read_b128 v[194:197], v141 offset:24944
	v_add_f32_e32 v201, 1.0, v201
	v_log_f32_e32 v201, v201
	s_waitcnt lgkmcnt(4)
	v_fmac_f32_e32 v52, v32, v66
	v_fmac_f32_e32 v53, v33, v64
	v_fmac_f32_e32 v52, v34, v70
	v_fmac_f32_e32 v53, v35, v68
	v_fmac_f32_e32 v52, v48, v67
	v_fmac_f32_e32 v53, v49, v65
	v_fmac_f32_e32 v52, v50, v71
	v_fmac_f32_e32 v53, v51, v69
	ds_read_b128 v[32:35], v141 offset:24960
	ds_read_b128 v[48:51], v141 offset:24976
	v_fmamk_f32 v43, v201, 0xbd800000, v42
	v_add_f32_e32 v200, v52, v53
	v_mul_f32_e32 v200, 0xbfb8aa3b, v200
	v_exp_f32_e32 v200, v200
	s_waitcnt lgkmcnt(4)
	v_fma_f32 v198, v182, v58, v127
	v_mul_f32_e32 v199, v183, v56
	v_fmac_f32_e32 v198, v184, v62
	v_fmac_f32_e32 v199, v185, v60
	v_fmac_f32_e32 v198, v186, v59
	v_fmac_f32_e32 v199, v187, v57
	v_fmac_f32_e32 v198, v188, v63
	v_fmac_f32_e32 v199, v189, v61
	ds_read_b128 v[182:185], v141 offset:24992
	ds_read_b128 v[186:189], v141 offset:25008
	v_add_f32_e32 v200, 1.0, v200
	v_log_f32_e32 v200, v200
	s_waitcnt lgkmcnt(4)
	v_fmac_f32_e32 v198, v190, v66
	v_fmac_f32_e32 v199, v191, v64
	v_fmac_f32_e32 v198, v192, v70
	v_fmac_f32_e32 v199, v193, v68
	v_fmac_f32_e32 v198, v194, v67
	v_fmac_f32_e32 v199, v195, v65
	v_fmac_f32_e32 v198, v196, v71
	v_fmac_f32_e32 v199, v197, v69
	ds_read_b128 v[190:193], v141 offset:25024
	ds_read_b128 v[194:197], v141 offset:25040
	v_fmamk_f32 v44, v200, 0xbd800000, v43
	v_add_f32_e32 v201, v198, v199
	v_mul_f32_e32 v201, 0xbfb8aa3b, v201
	v_exp_f32_e32 v201, v201
	s_waitcnt lgkmcnt(4)
	v_fma_f32 v52, v32, v58, v127
	v_mul_f32_e32 v53, v33, v56
	v_fmac_f32_e32 v52, v34, v62
	v_fmac_f32_e32 v53, v35, v60
	v_fmac_f32_e32 v52, v48, v59
	v_fmac_f32_e32 v53, v49, v57
	v_fmac_f32_e32 v52, v50, v63
	v_fmac_f32_e32 v53, v51, v61
	ds_read_b128 v[32:35], v141 offset:25056
	ds_read_b128 v[48:51], v141 offset:25072
	v_add_f32_e32 v201, 1.0, v201
	v_log_f32_e32 v201, v201
	s_waitcnt lgkmcnt(4)
	v_fmac_f32_e32 v52, v182, v66
	v_fmac_f32_e32 v53, v183, v64
	v_fmac_f32_e32 v52, v184, v70
	v_fmac_f32_e32 v53, v185, v68
	v_fmac_f32_e32 v52, v186, v67
	v_fmac_f32_e32 v53, v187, v65
	v_fmac_f32_e32 v52, v188, v71
	v_fmac_f32_e32 v53, v189, v69
	v_fmamk_f32 v45, v201, 0xbd800000, v44
	v_add_f32_e32 v200, v52, v53
	v_mul_f32_e32 v200, 0xbfb8aa3b, v200
	v_exp_f32_e32 v200, v200
	s_waitcnt lgkmcnt(2)
	v_fma_f32 v198, v190, v58, v127
	v_mul_f32_e32 v199, v191, v56
	v_fmac_f32_e32 v198, v192, v62
	v_fmac_f32_e32 v199, v193, v60
	v_fmac_f32_e32 v198, v194, v59
	v_fmac_f32_e32 v199, v195, v57
	v_fmac_f32_e32 v198, v196, v63
	v_fmac_f32_e32 v199, v197, v61
	v_add_f32_e32 v200, 1.0, v200
	v_log_f32_e32 v200, v200
	s_waitcnt lgkmcnt(0)
	v_fmac_f32_e32 v198, v32, v66
	v_fmac_f32_e32 v199, v33, v64
	v_fmac_f32_e32 v198, v34, v70
	v_fmac_f32_e32 v199, v35, v68
	v_fmac_f32_e32 v198, v48, v67
	v_fmac_f32_e32 v199, v49, v65
	v_fmac_f32_e32 v198, v50, v71
	v_fmac_f32_e32 v199, v51, v69
	v_fmamk_f32 v46, v200, 0xbd800000, v45
	v_add_f32_e32 v201, v198, v199
	v_mul_f32_e32 v201, 0xbfb8aa3b, v201
	v_exp_f32_e32 v201, v201
	s_nop 0
	v_add_f32_e32 v201, 1.0, v201
	v_log_f32_e32 v201, v201
	s_nop 0
	v_fmamk_f32 v47, v201, 0xbd800000, v46
	ds_write_b32 v129, v47 offset:23808
